# hg_prep (P4a): next unit's four 16-byte loads issued one unit ahead into spare registers
# speedup vs baseline: 1.0298x; 1.0071x over previous
; #define GAS __attribute__((address_space(1)))
; __device__ __forceinline__ void hg_prep(const Frame& F, unsigned char* ws, unsigned char* sfr) {
;     ...
;     for (int u = F.vcu; u < 2048 + NSEQ_S; u += F.G) {
;         int t0, nvalid, h; unsigned char *qf, *vf, *lf; int qp, lp;
;         if (u < 2048) { const int b = u >> 8, n = u & 63; h = (u >> 6) & 3; t0 = b * 2048 + n * 32; nvalid = 32;
;             const size_t e0 = (size_t)t0 * DA + h * 128; qf = ws + WS_Q + e0 * 2; vf = ws + WS_V + e0 * 2; lf = ws + WS_LOGF + e0 * 4; qp = 1024; lp = 2048; }
;         else { const int su = u - 2048, b = su >> 2; h = su & 3; t0 = TP + b * 8; nvalid = 8;
;             unsigned char* base = sfr + (size_t)su * 65536; qf = base; vf = base + 8192; lf = base + 16384; qp = 256; lp = 512; }
;         f32x4 lf0 = {0.f, 0.f, 0.f, 0.f}, lf1 = {0.f, 0.f, 0.f, 0.f}; v4u q8 = {0u, 0u, 0u, 0u}, v8 = {0u, 0u, 0u, 0u};
;         if (c < nvalid) { const size_t e = (size_t)(t0 + c) * DA + h * 128 + 8 * kg;
;             lf0 = NTL((const GAS f32x4*)(LFg + e)); lf1 = NTL((const GAS f32x4*)(LFg + e + 4)); q8 = NTL((const GAS v4u*)(Qg + e)); v8 = NTL((const GAS v4u*)(Vg + e)); }
.LBB0_431:
	s_cmpk_gt_i32 s33, 0x9ff
	s_cbranch_scc1 .LBB0_454
	s_add_u32 s3, s20, 0x4608000
	s_addc_u32 s19, s21, 0
	s_add_u32 s36, s22, 0xb980000
	s_addc_u32 s37, s23, 0
	s_add_u32 s38, s22, 0xca80000
	s_addc_u32 s39, s23, 0
	s_add_u32 s40, s22, 0xdb80000
	s_addc_u32 s41, s23, 0
	v_ashrrev_i32_e32 v1, 4, v188
	s_movk_i32 s6, 0x210
	s_cmp_gt_i32 s50, 3
	v_and_b32_e32 v5, 15, v188
	v_mul_lo_u32 v2, v1, s6
	s_cselect_b64 s[44:45], -1, 0
	s_cmp_lg_u32 s50, 1
	v_add_u32_e32 v2, 0, v2
	v_lshlrev_b32_e32 v3, 5, v5
	s_cselect_b64 s[46:47], -1, 0
	s_lshl_b32 s11, s50, 3
	v_add_u32_e32 v23, v2, v3
	v_add_u32_e32 v39, 0, v3
	v_lshlrev_b32_e32 v3, 8, v1
	v_lshlrev_b32_e32 v7, 4, v188
	v_and_b32_e32 v11, 15, v189
	s_and_b32 s12, s11, -16
	v_bfi_b32 v12, -16, s11, v189
	s_movk_i32 s11, 0x110
	s_lshl_b32 s13, s50, 4
	v_sub_u32_e32 v2, v2, v3
	s_movk_i32 s10, 0xfef2
	v_and_b32_e32 v6, 15, v1
	v_and_b32_e32 v8, 0xc0, v7
	v_and_b32_e32 v9, 0xfffff00, v188
	v_mul_lo_u32 v12, v12, s11
	v_and_b32_e32 v13, 48, v189
	v_and_or_b32 v11, s13, 16, v11
	v_lshl_add_u32 v40, v5, 4, v2
	v_mad_u64_u32 v[2:3], s[8:9], v1, s10, v[2:3]
	v_or3_b32 v6, v6, v9, v8
	v_add3_u32 v41, 0, v12, v13
	v_mad_u32_u24 v12, v11, s11, 0
	v_lshlrev_b32_e32 v4, 2, v188
	v_lshlrev_b32_e32 v3, 9, v188
	v_add_u32_e32 v42, v12, v13
	v_lshrrev_b32_e32 v13, 2, v189
	v_mad_i32_i24 v12, v11, s10, v12
	v_lshrrev_b32_e32 v15, 2, v188
	s_mov_b32 s10, 0xffffff0
	v_lshlrev_b32_e32 v6, 4, v6
	s_movk_i32 s11, 0x200
	v_and_b32_e32 v8, 8, v4
	v_add_u32_e32 v9, 0xffffff00, v188
	v_and_or_b32 v13, v13, 12, s12
	v_and_or_b32 v15, v15, s10, v5
	s_movk_i32 s12, 0x50
	v_and_or_b32 v3, v3, s11, v6
	s_movk_i32 s11, 0xf0
	v_and_b32_e32 v10, 48, v188
	v_add_u32_e32 v14, 0x2000, v7
	v_mul_lo_u32 v15, v15, s12
	v_and_or_b32 v28, v6, s11, v8
	v_lshrrev_b32_e32 v6, 2, v9
	v_lshlrev_b32_e32 v22, 3, v5
	v_add_u32_e32 v38, 0, v4
	v_add_u32_e32 v4, 0, v10
	v_add3_u32 v43, 0, v15, v10
	v_ashrrev_i32_e32 v44, 9, v14
	v_mul_u32_u24_e32 v10, 0x280, v5
	v_mul_u32_u24_e32 v14, 0x260, v5
	v_and_or_b32 v5, v6, s10, v5
	v_ashrrev_i32_e32 v46, 8, v3
	v_lshlrev_b32_e32 v3, 4, v9
	v_mad_u64_u32 v[30:31], s[10:11], v5, s12, v[4:5]
	v_add_u32_e32 v49, v4, v15
	v_or_b32_e32 v4, 1, v13
	v_and_b32_e32 v32, 0x1f0, v3
	v_and_b32_e32 v34, 0xf0, v3
	v_mul_lo_u32 v3, v13, s12
	v_cmp_lt_i32_e64 s[12:13], v4, v11
	v_or_b32_e32 v4, 2, v13
	v_mov_b32_e32 v25, 0
	s_movk_i32 s6, 0x80
	v_lshlrev_b32_e32 v16, 1, v1
	v_cmp_lt_i32_e64 s[14:15], v4, v11
	v_or_b32_e32 v4, 3, v13
	s_mov_b32 s43, 0
	v_cmp_gt_i32_e64 s[6:7], s6, v188
	v_cmp_gt_u32_e64 s[8:9], 16, v188
	v_lshlrev_b32_e32 v24, 5, v188
	v_and_b32_e32 v26, 0x1f0, v7
	v_mov_b32_e32 v27, v25
	v_add3_u32 v45, v39, v14, v16
	v_mov_b32_e32 v29, v25
	v_or_b32_e32 v47, 1, v46
	v_bfe_i32 v31, v9, 5, 23
	v_mov_b32_e32 v33, v25
	v_bfe_i32 v48, v9, 4, 24
	v_mov_b32_e32 v35, v25
	v_bfe_i32 v50, v188, 5, 23
	v_bfe_i32 v51, v188, 4, 24
	v_and_b32_e32 v36, 0xf0, v7
	v_mov_b32_e32 v37, v25
	v_cmp_lt_i32_e64 s[10:11], v13, v11
	v_cmp_lt_i32_e64 s[16:17], v4, v11
	s_movk_i32 s62, 0x7fff
	v_add_u32_e32 v52, v2, v10
	v_add_u32_e32 v53, v12, v3
	s_mov_b32 s63, s33
	s_mov_b32 s98, s63
	s_cmpk_gt_i32 s98, 0x7ff
	s_cbranch_scc1 .Lhgpf_smp_a
	s_lshl_b32 s99, s98, 3
	s_and_b32 s99, s99, 0xfffff800
	s_lshl_b32 s100, s98, 5
	s_and_b32 s100, s100, 0x7e0
	s_or_b32 s99, s99, s100
	s_bfe_u32 s100, s98, 0x20006
	s_movk_i32 s101, 32
	s_branch .Lhgpf_go_a
.Lhgpf_smp_a:
	s_add_i32 s99, s98, 0xfffff800
	s_lshl_b32 s99, s99, 1
	s_and_b32 s99, s99, 0x7ffffff8
	s_addk_i32 s99, 0x4000
	s_and_b32 s100, s98, 3
	s_movk_i32 s101, 8
.Lhgpf_go_a:
	v_mov_b32_e32 v200, 0
	v_mov_b32_e32 v201, 0
	v_mov_b32_e32 v202, 0
	v_mov_b32_e32 v203, 0
	v_mov_b32_e32 v204, 0
	v_mov_b32_e32 v205, 0
	v_mov_b32_e32 v206, 0
	v_mov_b32_e32 v207, 0
	v_mov_b32_e32 v208, 0
	v_mov_b32_e32 v209, 0
	v_mov_b32_e32 v210, 0
	v_mov_b32_e32 v211, 0
	v_mov_b32_e32 v212, 0
	v_mov_b32_e32 v213, 0
	v_mov_b32_e32 v214, 0
	v_mov_b32_e32 v215, 0
	v_add_u32_e32 v216, s99, v1
	v_lshlrev_b32_e32 v216, 9, v216
	s_lshl_b32 s100, s100, 7
	v_or3_b32 v216, v216, s100, v22
	v_lshlrev_b32_e32 v217, 2, v216
	v_lshlrev_b32_e32 v216, 1, v216
	v_cmp_gt_i32_e32 vcc, s101, v1
	s_and_saveexec_b64 s[100:101], vcc
	global_load_dwordx4 v[204:207], v217, s[40:41] offset:16
	global_load_dwordx4 v[200:203], v217, s[40:41]
	global_load_dwordx4 v[208:211], v216, s[36:37]
	global_load_dwordx4 v[212:215], v216, s[38:39]
	s_or_b64 exec, exec, s[100:101]
	s_branch .LBB0_434

; #define GAS __attribute__((address_space(1)))
; __device__ __forceinline__ void hg_prep(const Frame& F, unsigned char* ws, unsigned char* sfr) {
;     ...
;     for (int u = F.vcu; u < 2048 + NSEQ_S; u += F.G) {
;         int t0, nvalid, h; unsigned char *qf, *vf, *lf; int qp, lp;
;         if (u < 2048) { const int b = u >> 8, n = u & 63; h = (u >> 6) & 3; t0 = b * 2048 + n * 32; nvalid = 32;
;             const size_t e0 = (size_t)t0 * DA + h * 128; qf = ws + WS_Q + e0 * 2; vf = ws + WS_V + e0 * 2; lf = ws + WS_LOGF + e0 * 4; qp = 1024; lp = 2048; }
;         else { const int su = u - 2048, b = su >> 2; h = su & 3; t0 = TP + b * 8; nvalid = 8;
;             unsigned char* base = sfr + (size_t)su * 65536; qf = base; vf = base + 8192; lf = base + 16384; qp = 256; lp = 512; }
;         f32x4 lf0 = {0.f, 0.f, 0.f, 0.f}, lf1 = {0.f, 0.f, 0.f, 0.f}; v4u q8 = {0u, 0u, 0u, 0u}, v8 = {0u, 0u, 0u, 0u};
;         if (c < nvalid) { const size_t e = (size_t)(t0 + c) * DA + h * 128 + 8 * kg;
;             lf0 = NTL((const GAS f32x4*)(LFg + e)); lf1 = NTL((const GAS f32x4*)(LFg + e + 4)); q8 = NTL((const GAS v4u*)(Qg + e)); v8 = NTL((const GAS v4u*)(Vg + e)); }
.LBB0_439:
	s_waitcnt vmcnt(0)
	v_mov_b32_e32 v18, v200
	v_mov_b32_e32 v19, v201
	v_mov_b32_e32 v20, v202
	v_mov_b32_e32 v21, v203
	v_mov_b32_e32 v2, v204
	v_mov_b32_e32 v3, v205
	v_mov_b32_e32 v4, v206
	v_mov_b32_e32 v5, v207
	v_mov_b32_e32 v6, v208
	v_mov_b32_e32 v7, v209
	v_mov_b32_e32 v8, v210
	v_mov_b32_e32 v9, v211
	v_mov_b32_e32 v10, v212
	v_mov_b32_e32 v11, v213
	v_mov_b32_e32 v12, v214
	v_mov_b32_e32 v13, v215
	s_add_i32 s98, s63, s18
	s_cmpk_lt_i32 s98, 0xa00
	s_cbranch_scc0 .Lhgpf_none
	s_cmpk_gt_i32 s98, 0x7ff
	s_cbranch_scc1 .Lhgpf_smp_b
	s_lshl_b32 s99, s98, 3
	s_and_b32 s99, s99, 0xfffff800
	s_lshl_b32 s100, s98, 5
	s_and_b32 s100, s100, 0x7e0
	s_or_b32 s99, s99, s100
	s_bfe_u32 s100, s98, 0x20006
	s_movk_i32 s101, 32
	s_branch .Lhgpf_go_b

; #define GAS __attribute__((address_space(1)))
; #define LAS __attribute__((address_space(3)))
; #define VM_WAIT() asm volatile("s_waitcnt vmcnt(0)" ::: "memory")
; __device__ __forceinline__ void hg_prep(const Frame& F, unsigned char* ws, unsigned char* sfr) {
;     ...
;         if (c < nvalid) { const size_t e = (size_t)(t0 + c) * DA + h * 128 + 8 * kg;
;             lf0 = NTL((const GAS f32x4*)(LFg + e)); lf1 = NTL((const GAS f32x4*)(LFg + e + 4)); q8 = NTL((const GAS v4u*)(Qg + e)); v8 = NTL((const GAS v4u*)(Vg + e)); }
;         VM_WAIT();
;         *(LAS f32x4*)(LB + c * 132 + 8 * kg) = lf0; *(LAS f32x4*)(LB + c * 132 + 8 * kg + 4) = lf1;
;         { const unsigned vv[4] = {v8.x, v8.y, v8.z, v8.w};
; #pragma unroll
;           for (int j = 0; j < 4; ++j) { VT[(8 * kg + 2 * j) * 40 + c] = (bf16)(vv[j] & 0xffffu); VT[(8 * kg + 2 * j + 1) * 40 + c] = (bf16)(vv[j] >> 16); } }
.Lhgpf_go_b:
	v_mov_b32_e32 v200, 0
	v_mov_b32_e32 v201, 0
	v_mov_b32_e32 v202, 0
	v_mov_b32_e32 v203, 0
	v_mov_b32_e32 v204, 0
	v_mov_b32_e32 v205, 0
	v_mov_b32_e32 v206, 0
	v_mov_b32_e32 v207, 0
	v_mov_b32_e32 v208, 0
	v_mov_b32_e32 v209, 0
	v_mov_b32_e32 v210, 0
	v_mov_b32_e32 v211, 0
	v_mov_b32_e32 v212, 0
	v_mov_b32_e32 v213, 0
	v_mov_b32_e32 v214, 0
	v_mov_b32_e32 v215, 0
	v_add_u32_e32 v216, s99, v1
	v_lshlrev_b32_e32 v216, 9, v216
	s_lshl_b32 s100, s100, 7
	v_or3_b32 v216, v216, s100, v22
	v_lshlrev_b32_e32 v217, 2, v216
	v_lshlrev_b32_e32 v216, 1, v216
	v_cmp_gt_i32_e32 vcc, s101, v1
	s_and_saveexec_b64 s[100:101], vcc
	global_load_dwordx4 v[204:207], v217, s[40:41] offset:16
	global_load_dwordx4 v[200:203], v217, s[40:41]
	global_load_dwordx4 v[208:211], v216, s[36:37]
	global_load_dwordx4 v[212:215], v216, s[38:39]
	s_or_b64 exec, exec, s[100:101]
.Lhgpf_none:
.LBB0_441:
	ds_write_b128 v23, v[18:21]
	ds_write_b128 v23, v[2:5] offset:16
	ds_write_b16 v45, v10 offset:44544
	ds_write_b16_d16_hi v45, v10 offset:44624
	ds_write_b16 v45, v11 offset:44704
	ds_write_b16_d16_hi v45, v11 offset:44784
	ds_write_b16 v45, v12 offset:44864
	ds_write_b16_d16_hi v45, v12 offset:44944
	ds_write_b16 v45, v13 offset:45024
	ds_write_b16_d16_hi v45, v13 offset:45104
	s_waitcnt lgkmcnt(0)
	s_barrier
	s_and_saveexec_b64 s[58:59], s[6:7]
	s_cbranch_execz .LBB0_444
	v_mov_b32_e32 v10, 0
	s_mov_b32 s42, 0
